# group and panel barriers: waiters poll the arrival counter itself (one L2 hop fewer than waiting for the release word)
# speedup vs baseline: 1.0097x; 1.0097x over previous
.LBB0_186:
	s_or_b64 exec, exec, s[6:7]
	s_waitcnt vmcnt(0)
	v_readfirstlane_b32 s4, v2
	s_mov_b64 s[6:7], -1
	s_nop 0
	v_add_u32_e32 v0, s4, v0
	v_readlane_b32 s4, v251, 60
	v_and_b32_e32 v2, 3, v0
	v_readlane_b32 s5, v251, 61
	v_cmp_ne_u32_e32 vcc, 3, v2
	s_nop 0
	v_mov_b64_e32 v[2:3], s[4:5]
	s_and_saveexec_b64 s[4:5], vcc
	s_cbranch_execz .LBB0_198
	v_readlane_b32 s6, v251, 58
	v_readlane_b32 s7, v251, 59
	v_lshrrev_b32_e32 v0, 2, v0
	s_mov_b64 s[8:9], 0
	s_nop 2
	global_load_dword v2, v1, s[6:7] sc1
	s_waitcnt vmcnt(0)
	v_lshrrev_b32_e32 v2, 2, v2
	v_cmp_eq_u32_e32 vcc, v2, v0
	s_and_saveexec_b64 s[6:7], vcc
	s_cbranch_execz .LBB0_197
	s_mov_b32 s13, 1
	s_branch .LBB0_190

.LBB0_194:
	v_readlane_b32 s14, v251, 58
	v_readlane_b32 s15, v251, 59
	s_add_i32 s13, s13, 1
	s_mov_b64 s[38:39], -1
	s_nop 2
	global_load_dword v2, v1, s[14:15] sc1
	s_waitcnt vmcnt(0)
	v_lshrrev_b32_e32 v2, 2, v2
	v_cmp_ne_u32_e32 vcc, v2, v0
	s_orn2_b64 s[36:37], vcc, exec
	s_branch .LBB0_189

.LBB0_329:
	v_readlane_b32 s14, v251, 58
	v_readlane_b32 s15, v251, 59
	s_add_i32 s13, s13, 1
	s_mov_b64 s[40:41], -1
	s_nop 2
	global_load_dword v2, v1, s[14:15] sc1
	s_waitcnt vmcnt(0)
	v_lshrrev_b32_e32 v2, 2, v2
	v_cmp_ne_u32_e32 vcc, v2, v0
	s_orn2_b64 s[36:37], vcc, exec
	s_branch .LBB0_324

.LBB0_425:
	s_or_b64 exec, exec, s[8:9]
	s_waitcnt vmcnt(0)
	v_readfirstlane_b32 s1, v2
	s_mov_b64 s[8:9], -1
	s_nop 0
	v_add_u32_e32 v0, s1, v0
	v_readlane_b32 s0, v252, 54
	v_and_b32_e32 v2, 31, v0
	v_readlane_b32 s1, v252, 55
	v_cmp_ne_u32_e32 vcc, 31, v2
	s_nop 0
	v_mov_b64_e32 v[2:3], s[0:1]
	s_and_saveexec_b64 s[6:7], vcc
	s_cbranch_execz .LBB0_437
	v_readlane_b32 s0, v252, 52
	v_readlane_b32 s1, v252, 53
	v_lshrrev_b32_e32 v0, 5, v0
	s_mov_b64 s[10:11], 0
	s_nop 2
	global_load_dword v2, v1, s[0:1] sc1
	s_waitcnt vmcnt(0)
	v_lshrrev_b32_e32 v2, 5, v2
	v_cmp_eq_u32_e32 vcc, v2, v0
	s_and_saveexec_b64 s[8:9], vcc
	s_cbranch_execz .LBB0_436
	s_mov_b32 s1, 1
	s_branch .LBB0_429

.LBB0_433:
	v_readlane_b32 s2, v252, 52
	v_readlane_b32 s3, v252, 53
	s_add_i32 s1, s1, 1
	s_mov_b64 s[42:43], -1
	s_nop 2
	global_load_dword v2, v1, s[2:3] sc1
	s_waitcnt vmcnt(0)
	v_lshrrev_b32_e32 v2, 5, v2
	v_cmp_ne_u32_e32 vcc, v2, v0
	s_orn2_b64 s[40:41], vcc, exec
	s_branch .LBB0_428

.LBB0_535:
	s_or_b64 exec, exec, s[6:7]
	s_waitcnt vmcnt(0)
	v_readfirstlane_b32 s4, v2
	s_mov_b64 s[6:7], -1
	s_nop 0
	v_add_u32_e32 v0, s4, v0
	v_readlane_b32 s4, v252, 54
	v_and_b32_e32 v2, 31, v0
	v_readlane_b32 s5, v252, 55
	v_cmp_ne_u32_e32 vcc, 31, v2
	s_nop 0
	v_mov_b64_e32 v[2:3], s[4:5]
	s_and_saveexec_b64 s[4:5], vcc
	s_cbranch_execz .LBB0_547
	v_readlane_b32 s6, v252, 52
	v_readlane_b32 s7, v252, 53
	v_lshrrev_b32_e32 v0, 5, v0
	s_mov_b64 s[8:9], 0
	s_nop 2
	global_load_dword v2, v1, s[6:7] sc1
	s_waitcnt vmcnt(0)
	v_lshrrev_b32_e32 v2, 5, v2
	v_cmp_eq_u32_e32 vcc, v2, v0
	s_and_saveexec_b64 s[6:7], vcc
	s_cbranch_execz .LBB0_546
	s_mov_b32 s13, 1
	s_branch .LBB0_539

.LBB0_543:
	v_readlane_b32 s14, v252, 52
	v_readlane_b32 s15, v252, 53
	s_add_i32 s13, s13, 1
	s_mov_b64 s[40:41], -1
	s_nop 2
	global_load_dword v2, v1, s[14:15] sc1
	s_waitcnt vmcnt(0)
	v_lshrrev_b32_e32 v2, 5, v2
	v_cmp_ne_u32_e32 vcc, v2, v0
	s_orn2_b64 s[36:37], vcc, exec
	s_branch .LBB0_538

.LBB0_653:
	v_readlane_b32 s14, v252, 52
	v_readlane_b32 s15, v252, 53
	s_add_i32 s13, s13, 1
	s_mov_b64 s[38:39], -1
	s_nop 2
	global_load_dword v2, v1, s[14:15] sc1
	s_waitcnt vmcnt(0)
	v_lshrrev_b32_e32 v2, 5, v2
	v_cmp_ne_u32_e32 vcc, v2, v0
	s_orn2_b64 s[36:37], vcc, exec
	s_branch .LBB0_648

.LBB0_1063:
	v_readlane_b32 s14, v251, 58
	v_readlane_b32 s15, v251, 59
	s_add_i32 s13, s13, 1
	s_mov_b64 s[40:41], -1
	s_nop 2
	global_load_dword v2, v1, s[14:15] sc1
	s_waitcnt vmcnt(0)
	v_lshrrev_b32_e32 v2, 2, v2
	v_cmp_ne_u32_e32 vcc, v2, v0
	s_orn2_b64 s[38:39], vcc, exec
	s_branch .LBB0_1058
